# lever 4: static s_setprio 1 for waves 4-7 (second wave per SIMD) across the per-block tail GEMM chain, reset at tail exit
# speedup vs baseline: 1.0004x; 1.0004x over previous
; DI int otid() { int t = (int)__builtin_amdgcn_workitem_id_x(); asm volatile("" : "+v"(t)); return t; }
; DI void phase_tail(const Ctx& c) {
;   bf16* lds = (bf16*)c.smem;
;   float* rstd = (float*)(c.smem + GEMM3_LDS); float* rowss = rstd + 128; float* rstd2 = rowss + 512;
;   const bf16* W = (const bf16*)(c.ws + OFF_W + c.layer * SZ_WL);
;   bf16* MERGED = (bf16*)(c.ws + OFF_MERGED);
;   bf16* F = (bf16*)(c.ws + OFF_F);
;   bf16* XB = (bf16*)(c.ws + OFF_XB);
;   const int tid = otid(), lane = tid & 63, wave = tid >> 6, wm = wave >> 2, wn = wave & 3;
;   for (int mt = blockIdx.x; mt < 256; mt += gridDim.x) {
;     const int m0 = mt * 128;
;     post_mix_rows(c, m0);
;     compute_rstd2<float>(c.xin + (size_t)m0 * DM, DM, DM, rstd, 128);
;     for (int nt = 0; nt < 8; ++nt) {
;       const int wm2 = wave >> 1;
.LBB0_788:
	s_or_b64 exec, exec, s[0:1]
	v_readlane_b32 s0, v229, 20
	v_readlane_b32 s1, v229, 21
	v_mov_b32_e32 v0, v186
	s_andn2_b64 vcc, exec, s[0:1]
	s_barrier
	s_cbranch_vccnz .LBB0_901
	v_readfirstlane_b32 s100, v186
	s_cmpk_lt_u32 s100, 0x100
	s_cbranch_scc1 .Ltailprio_lo
	s_setprio 1
.Ltailprio_lo:
	v_readlane_b32 s4, v226, 21
	v_readlane_b32 s5, v226, 22
	s_add_u32 s49, s4, 0x840000
	s_addc_u32 s50, s5, 0
	s_add_u32 s51, s4, 0xee0000
	s_addc_u32 s52, s5, 0
	s_add_u32 s53, s4, 0x11e0000
	s_addc_u32 s54, s5, 0
	v_lshrrev_b32_e32 v3, 2, v0
	s_add_u32 s55, s4, 0x13e0000
	v_ashrrev_i32_e32 v2, 2, v0
	v_and_b32_e32 v3, 12, v3
	s_addc_u32 s90, s5, 0
	s_movk_i32 s0, 0xffc0
	v_and_or_b32 v2, v2, s0, v3
	s_add_u32 s91, s4, 0x1ee0000
	s_mov_b32 s0, 0x24000
	s_addc_u32 s4, s5, 0
	v_and_b32_e32 v4, 0xffffff80, v0
	s_addk_i32 s0, 0x50
	v_lshlrev_b32_e32 v3, 2, v3
	v_add3_u32 v142, s0, v4, v3
	v_readlane_b32 s0, v227, 35
	v_readlane_b32 s8, v229, 22
	v_readlane_b32 s9, v229, 23
	v_lshl_add_u32 v143, v2, 2, s0
	s_movk_i32 s0, 0x88
	v_mul_lo_u32 v2, v2, s0
	v_and_or_b32 v2, v0, 15, v2
	v_readlane_b32 s10, v229, 24
	v_readlane_b32 s11, v229, 25
	v_readlane_b32 s12, v229, 26
	v_readlane_b32 s13, v229, 27
	v_readlane_b32 s14, v229, 28
	v_readlane_b32 s15, v229, 29
	v_readlane_b32 s16, v229, 30
	v_readlane_b32 s17, v229, 31
	v_lshlrev_b32_e32 v2, 1, v2
	v_and_b32_e32 v0, 0xc0, v0
	s_movk_i32 s0, 0x50
	s_lshl_b32 s82, s24, 7
	v_readlane_b32 s18, v229, 32
	v_readlane_b32 s19, v229, 33
	v_readlane_b32 s20, v229, 34
	v_readlane_b32 s21, v229, 35
	v_readlane_b32 s22, v229, 36
	v_readlane_b32 s23, v229, 37
	s_mov_b64 s[8:9], s[16:17]
	v_add3_u32 v144, s0, v2, v0
	s_lshl_b64 s[0:1], s[82:83], 2
	s_mov_b64 s[14:15], s[22:23]
	s_add_u32 s0, s14, s0
	s_mov_b64 s[10:11], s[18:19]
	s_mov_b64 s[12:13], s[20:21]
	s_addc_u32 s1, s15, s1
	v_writelane_b32 v226, s0, 35
	s_lshl_b32 s82, s24, 10
	v_readlane_b32 s8, v229, 38
	v_writelane_b32 v226, s1, 36
	s_lshl_b64 s[0:1], s[82:83], 2
	v_readlane_b32 s14, v229, 44
	v_readlane_b32 s15, v229, 45
	s_add_u32 s6, s14, s0
	v_readlane_b32 s18, v229, 48
	s_addc_u32 s7, s15, s1
	v_readlane_b32 s9, v229, 39
	v_readlane_b32 s19, v229, 49
	s_add_u32 s8, s18, s0
	v_readlane_b32 s10, v229, 40
	s_addc_u32 s9, s19, s1
	v_readlane_b32 s0, v227, 18
	v_readlane_b32 s1, v226, 25
	v_readlane_b32 s11, v229, 41
	s_add_u32 s10, s0, s1
	v_readlane_b32 s0, v227, 19
	s_addc_u32 s11, s0, 0
	v_writelane_b32 v226, s10, 29
	v_readlane_b32 s0, v227, 22
	v_readlane_b32 s16, v229, 46
	v_writelane_b32 v226, s11, 30
	s_add_u32 s10, s0, s1
	v_readlane_b32 s0, v227, 23
	s_addc_u32 s11, s0, 0
	v_writelane_b32 v226, s10, 31
	v_readlane_b32 s0, v227, 24
	v_readlane_b32 s13, v229, 43
	v_writelane_b32 v226, s11, 32
	s_add_u32 s10, s0, s1
	v_readlane_b32 s0, v227, 25
	s_addc_u32 s11, s0, 0
	v_readlane_b32 s0, v227, 16
	s_mov_b32 s16, s0
	v_readlane_b32 s0, v227, 13
	v_add_u32_e32 v145, 0x110, v144
	v_add_u32_e32 v146, 0x220, v144
	v_add_u32_e32 v147, 0x330, v144
	v_add_u32_e32 v148, 64, v143
	v_add_u32_e32 v149, 0x1100, v144
	v_add_u32_e32 v150, 0x1210, v144
	v_add_u32_e32 v151, 0x1320, v144
	v_add_u32_e32 v152, 0x1430, v144
	v_add_u32_e32 v153, 0x80, v143
	v_add_u32_e32 v154, 0x2200, v144
	v_add_u32_e32 v155, 0x2310, v144
	v_add_u32_e32 v156, 0x2420, v144
	v_add_u32_e32 v157, 0x2530, v144
	v_add_u32_e32 v158, 0xc0, v143
	v_add_u32_e32 v159, 0x3300, v144
	v_add_u32_e32 v160, 0x3410, v144
	v_add_u32_e32 v161, 0x3520, v144
	v_add_u32_e32 v162, 0x3630, v144
	v_writelane_b32 v226, s10, 33
	v_readlane_b32 s48, v227, 17
	s_mov_b32 s13, s0
	v_readlane_b32 s12, v229, 42
	v_readlane_b32 s17, v229, 47
	v_readlane_b32 s20, v229, 50
	v_readlane_b32 s21, v229, 51
	v_readlane_b32 s22, v229, 52
	v_readlane_b32 s23, v229, 53
	v_writelane_b32 v226, s11, 34
	v_readlane_b32 s1, v227, 14
	s_branch .LBB0_791

; DI int otid() { int t = (int)__builtin_amdgcn_workitem_id_x(); asm volatile("" : "+v"(t)); return t; }
; DI void grid_barrier(unsigned* bar, unsigned nb, unsigned& target) {
;   asm volatile("s_waitcnt vmcnt(0) lgkmcnt(0)" ::: "memory");
;   __syncthreads();
;   target += nb;
;   if (otid() == 0) {
;     __builtin_amdgcn_fence(__ATOMIC_RELEASE, "agent");
;     asm volatile("s_waitcnt vmcnt(0)" ::: "memory");
;     __hip_atomic_fetch_add(bar, 1u, __ATOMIC_RELAXED, __HIP_MEMORY_SCOPE_AGENT);
;     while (__hip_atomic_load(bar, __ATOMIC_RELAXED, __HIP_MEMORY_SCOPE_AGENT) < target) __builtin_amdgcn_s_sleep(1);
.LBB0_901:
	s_setprio 0
	s_waitcnt vmcnt(0) lgkmcnt(0)
	v_mov_b32_e32 v0, v186
	s_barrier
	s_add_i32 s12, s39, s38
	s_nop 0
	v_cmp_eq_u32_e32 vcc, 0, v0
	s_and_saveexec_b64 s[0:1], vcc
	s_cbranch_execnz .LBB0_902
	s_getpc_b64 s[98:99]
